# StaticOrder tile split: generic 32-bit division replaced by shift/mask (group size is always 8) in the P1 and P5 unit headers
# speedup vs baseline: 1.0222x; 1.0040x over previous
;     __host__ __device__ bool next(int i, Unit& u) const {
;         const long L = (long)i * G + c; if (L >= nwg) return false;
;         int wgid = (int)L; { const int q = nwg / NXCD, r = nwg % NXCD, xcd = wgid % NXCD, off = wgid / NXCD; wgid = (xcd < r ? xcd * (q + 1) : r * (q + 1) + (xcd - r) * q) + off; }
;         const int nig = WGM * nN, gid = wgid / nig, fm = gid * WGM, gsz = (nM - fm) < WGM ? (nM - fm) : WGM;
;         u.pm = fm + ((wgid % nig) % gsz); u.pn = (wgid % nig) / gsz; return true;
.LBB0_107:
	s_add_i32 s91, s91, 1
	s_mul_i32 s1, s91, s96
	s_mul_hi_u32 s4, s91, s3
	s_add_i32 s4, s4, s1
	s_mul_i32 s1, s91, s3
	s_add_u32 s76, s1, s2
	s_addc_u32 s77, s4, s97
	v_cmp_gt_i64_e32 vcc, s[76:77], v[144:145]
	v_cmp_lt_i64_e64 s[4:5], s[76:77], v[142:143]
	s_cbranch_vccnz .LBB0_109
	s_ashr_i32 s1, s76, 31
	s_lshr_b32 s1, s1, 29
	s_add_i32 s1, s76, s1
	s_ashr_i32 s33, s1, 3
	s_and_b32 s1, s1, -8
	s_sub_i32 s1, s76, s1
	s_cmp_lt_i32 s1, 0
	s_movk_i32 s60, 0x59
	s_cselect_b32 s60, s60, 0x58
	s_mul_i32 s1, s1, s60
	s_add_i32 s1, s1, s33
	s_mul_hi_i32 s33, s1, 0x2e8ba2e9
	s_lshr_b32 s60, s33, 31
	s_ashr_i32 s33, s33, 4
	s_add_i32 s33, s33, s60
	s_lshl_b32 s60, s33, 3
	s_sub_i32 s61, 64, s60
	s_min_i32 s61, s61, 8
	s_mulk_i32 s33, 0x58
	s_sub_i32 s1, s1, s33
	s_lshr_b32 s72, s1, 3
	s_and_b32 s1, s1, 7
	s_add_i32 s74, s60, s1

;     __host__ __device__ bool next(int i, Unit& u) const {
;         const long L = (long)i * G + c; if (L >= nwg) return false;
;         int wgid = (int)L; { const int q = nwg / NXCD, r = nwg % NXCD, xcd = wgid % NXCD, off = wgid / NXCD; wgid = (xcd < r ? xcd * (q + 1) : r * (q + 1) + (xcd - r) * q) + off; }
;         const int nig = WGM * nN, gid = wgid / nig, fm = gid * WGM, gsz = (nM - fm) < WGM ? (nM - fm) : WGM;
;         u.pm = fm + ((wgid % nig) % gsz); u.pn = (wgid % nig) / gsz; return true;
.LBB0_737:
	s_add_i32 s69, s69, 1
	s_mul_i32 s0, s69, s63
	s_mul_hi_u32 s1, s69, s3
	s_add_i32 s1, s1, s0
	s_mul_i32 s0, s69, s3
	s_add_u32 s20, s0, s2
	s_addc_u32 s21, s1, s64
	v_cmp_gt_i64_e32 vcc, s[20:21], v[146:147]
	v_cmp_lt_i64_e64 s[0:1], s[20:21], v[144:145]
	s_cbranch_vccnz .LBB0_739
	s_ashr_i32 s16, s20, 31
	s_lshr_b32 s16, s16, 29
	s_add_i32 s16, s20, s16
	s_ashr_i32 s17, s16, 3
	s_and_b32 s16, s16, -8
	s_sub_i32 s16, s20, s16
	s_cmp_lt_i32 s16, 0
	s_cselect_b32 s18, s65, 0xb0
	s_mul_i32 s16, s16, s18
	s_add_i32 s16, s16, s17
	s_mul_hi_i32 s17, s16, 0x2e8ba2e9
	s_lshr_b32 s18, s17, 31
	s_ashr_i32 s17, s17, 5
	s_add_i32 s17, s17, s18
	s_lshl_b32 s18, s17, 3
	s_sub_i32 s19, 64, s18
	s_min_i32 s19, s19, 8
	s_mulk_i32 s17, 0xb0
	s_sub_i32 s17, s16, s17
	s_lshr_b32 s16, s17, 3
	s_and_b32 s17, s17, 7
	s_add_i32 s18, s18, s17
